# the six GEMM K-loop heads aligned to 64 bytes (s_nop fill)
# baseline (speedup 1.0000x reference)
.LBB0_164:
	s_ashr_i32 s13, s12, 31
	s_lshl_b64 s[14:15], s[12:13], 20
	s_add_u32 s14, s18, s14
	s_addc_u32 s15, s19, s15
	s_and_b64 s[20:21], s[0:1], exec
	s_cselect_b32 s13, s15, s27
	s_cselect_b32 s20, s14, s26
	s_ashr_i32 s11, s10, 31
	s_lshl_b64 s[22:23], s[10:11], 20
	s_add_u32 s84, s40, s22
	s_addc_u32 s85, s41, s23
	s_and_b64 s[22:23], s[0:1], exec
	s_cselect_b32 s11, s85, s29
	s_cselect_b32 s21, s84, s28
	s_add_u32 s26, s26, 0x80080
	s_addc_u32 s27, s27, 0
	s_add_u32 s22, s28, 0x100
	v_mov_b32_e32 v0, 0
	s_addc_u32 s23, s29, 0
	s_mov_b32 s24, -2
	v_mov_b32_e32 v1, v0
	v_mov_b32_e32 v2, v0
	v_mov_b32_e32 v3, v0
	v_mov_b32_e32 v8, v0
	v_mov_b32_e32 v9, v0
	v_mov_b32_e32 v10, v0
	v_mov_b32_e32 v11, v0
	v_mov_b32_e32 v16, v0
	v_mov_b32_e32 v17, v0
	v_mov_b32_e32 v18, v0
	v_mov_b32_e32 v19, v0
	v_mov_b32_e32 v24, v0
	v_mov_b32_e32 v25, v0
	v_mov_b32_e32 v26, v0
	v_mov_b32_e32 v27, v0
	v_mov_b32_e32 v32, v0
	v_mov_b32_e32 v33, v0
	v_mov_b32_e32 v34, v0
	v_mov_b32_e32 v35, v0
	v_mov_b32_e32 v40, v0
	v_mov_b32_e32 v41, v0
	v_mov_b32_e32 v42, v0
	v_mov_b32_e32 v43, v0
	v_mov_b32_e32 v48, v0
	v_mov_b32_e32 v49, v0
	v_mov_b32_e32 v50, v0
	v_mov_b32_e32 v51, v0
	v_mov_b32_e32 v56, v0
	v_mov_b32_e32 v57, v0
	v_mov_b32_e32 v58, v0
	v_mov_b32_e32 v59, v0
	v_mov_b32_e32 v4, v0
	v_mov_b32_e32 v5, v0
	v_mov_b32_e32 v6, v0
	v_mov_b32_e32 v7, v0
	v_mov_b32_e32 v12, v0
	v_mov_b32_e32 v13, v0
	v_mov_b32_e32 v14, v0
	v_mov_b32_e32 v15, v0
	v_mov_b32_e32 v20, v0
	v_mov_b32_e32 v21, v0
	v_mov_b32_e32 v22, v0
	v_mov_b32_e32 v23, v0
	v_mov_b32_e32 v28, v0
	v_mov_b32_e32 v29, v0
	v_mov_b32_e32 v30, v0
	v_mov_b32_e32 v31, v0
	v_mov_b32_e32 v36, v0
	v_mov_b32_e32 v37, v0
	v_mov_b32_e32 v38, v0
	v_mov_b32_e32 v39, v0
	v_mov_b32_e32 v44, v0
	v_mov_b32_e32 v45, v0
	v_mov_b32_e32 v46, v0
	v_mov_b32_e32 v47, v0
	v_mov_b32_e32 v52, v0
	v_mov_b32_e32 v53, v0
	v_mov_b32_e32 v54, v0
	v_mov_b32_e32 v55, v0
	v_mov_b32_e32 v60, v0
	v_mov_b32_e32 v61, v0
	v_mov_b32_e32 v62, v0
	v_mov_b32_e32 v63, v0
	v_mov_b32_e32 v64, v0
	v_mov_b32_e32 v65, v0
	v_mov_b32_e32 v66, v0
	v_mov_b32_e32 v67, v0
	v_mov_b32_e32 v72, v0
	v_mov_b32_e32 v73, v0
	v_mov_b32_e32 v74, v0
	v_mov_b32_e32 v75, v0
	v_mov_b32_e32 v80, v0
	v_mov_b32_e32 v81, v0
	v_mov_b32_e32 v82, v0
	v_mov_b32_e32 v83, v0
	v_mov_b32_e32 v88, v0
	v_mov_b32_e32 v89, v0
	v_mov_b32_e32 v90, v0
	v_mov_b32_e32 v91, v0
	v_mov_b32_e32 v96, v0
	v_mov_b32_e32 v97, v0
	v_mov_b32_e32 v98, v0
	v_mov_b32_e32 v99, v0
	v_mov_b32_e32 v104, v0
	v_mov_b32_e32 v105, v0
	v_mov_b32_e32 v106, v0
	v_mov_b32_e32 v107, v0
	v_mov_b32_e32 v112, v0
	v_mov_b32_e32 v113, v0
	v_mov_b32_e32 v114, v0
	v_mov_b32_e32 v115, v0
	v_mov_b32_e32 v120, v0
	v_mov_b32_e32 v121, v0
	v_mov_b32_e32 v122, v0
	v_mov_b32_e32 v123, v0
	v_mov_b32_e32 v68, v0
	v_mov_b32_e32 v69, v0
	v_mov_b32_e32 v70, v0
	v_mov_b32_e32 v71, v0
	v_mov_b32_e32 v76, v0
	v_mov_b32_e32 v77, v0
	v_mov_b32_e32 v78, v0
	v_mov_b32_e32 v79, v0
	v_mov_b32_e32 v84, v0
	v_mov_b32_e32 v85, v0
	v_mov_b32_e32 v86, v0
	v_mov_b32_e32 v87, v0
	v_mov_b32_e32 v92, v0
	v_mov_b32_e32 v93, v0
	v_mov_b32_e32 v94, v0
	v_mov_b32_e32 v95, v0
	v_mov_b32_e32 v100, v0
	v_mov_b32_e32 v101, v0
	v_mov_b32_e32 v102, v0
	v_mov_b32_e32 v103, v0
	v_mov_b32_e32 v108, v0
	v_mov_b32_e32 v109, v0
	v_mov_b32_e32 v110, v0
	v_mov_b32_e32 v111, v0
	v_mov_b32_e32 v116, v0
	v_mov_b32_e32 v117, v0
	v_mov_b32_e32 v118, v0
	v_mov_b32_e32 v119, v0
	v_mov_b32_e32 v124, v0
	v_mov_b32_e32 v125, v0
	v_mov_b32_e32 v126, v0
	v_mov_b32_e32 v127, v0
	.p2alignl 6, 3212836864

.LBB0_262:
	s_add_u32 s44, s28, 0x100
	v_mov_b32_e32 v0, 0
	s_addc_u32 s45, s29, 0
	s_mov_b32 s46, -2
	s_waitcnt lgkmcnt(0)
	v_mov_b32_e32 v1, v0
	v_mov_b32_e32 v2, v0
	v_mov_b32_e32 v3, v0
	v_mov_b32_e32 v4, v0
	v_mov_b32_e32 v5, v0
	v_mov_b32_e32 v6, v0
	v_mov_b32_e32 v7, v0
	v_mov_b32_e32 v16, v0
	v_mov_b32_e32 v17, v0
	v_mov_b32_e32 v18, v0
	v_mov_b32_e32 v19, v0
	v_mov_b32_e32 v20, v0
	v_mov_b32_e32 v21, v0
	v_mov_b32_e32 v22, v0
	v_mov_b32_e32 v23, v0
	v_mov_b32_e32 v32, v0
	v_mov_b32_e32 v33, v0
	v_mov_b32_e32 v34, v0
	v_mov_b32_e32 v35, v0
	v_mov_b32_e32 v36, v0
	v_mov_b32_e32 v37, v0
	v_mov_b32_e32 v38, v0
	v_mov_b32_e32 v39, v0
	v_mov_b32_e32 v48, v0
	v_mov_b32_e32 v49, v0
	v_mov_b32_e32 v50, v0
	v_mov_b32_e32 v51, v0
	v_mov_b32_e32 v52, v0
	v_mov_b32_e32 v53, v0
	v_mov_b32_e32 v54, v0
	v_mov_b32_e32 v55, v0
	v_mov_b32_e32 v8, v0
	v_mov_b32_e32 v9, v0
	v_mov_b32_e32 v10, v0
	v_mov_b32_e32 v11, v0
	v_mov_b32_e32 v12, v0
	v_mov_b32_e32 v13, v0
	v_mov_b32_e32 v14, v0
	v_mov_b32_e32 v15, v0
	v_mov_b32_e32 v24, v0
	v_mov_b32_e32 v25, v0
	v_mov_b32_e32 v26, v0
	v_mov_b32_e32 v27, v0
	v_mov_b32_e32 v28, v0
	v_mov_b32_e32 v29, v0
	v_mov_b32_e32 v30, v0
	v_mov_b32_e32 v31, v0
	v_mov_b32_e32 v40, v0
	v_mov_b32_e32 v41, v0
	v_mov_b32_e32 v42, v0
	v_mov_b32_e32 v43, v0
	v_mov_b32_e32 v44, v0
	v_mov_b32_e32 v45, v0
	v_mov_b32_e32 v46, v0
	v_mov_b32_e32 v47, v0
	v_mov_b32_e32 v56, v0
	v_mov_b32_e32 v57, v0
	v_mov_b32_e32 v58, v0
	v_mov_b32_e32 v59, v0
	v_mov_b32_e32 v60, v0
	v_mov_b32_e32 v61, v0
	v_mov_b32_e32 v62, v0
	v_mov_b32_e32 v63, v0
	v_mov_b32_e32 v64, v0
	v_mov_b32_e32 v65, v0
	v_mov_b32_e32 v66, v0
	v_mov_b32_e32 v67, v0
	v_mov_b32_e32 v68, v0
	v_mov_b32_e32 v69, v0
	v_mov_b32_e32 v70, v0
	v_mov_b32_e32 v71, v0
	v_mov_b32_e32 v80, v0
	v_mov_b32_e32 v81, v0
	v_mov_b32_e32 v82, v0
	v_mov_b32_e32 v83, v0
	v_mov_b32_e32 v84, v0
	v_mov_b32_e32 v85, v0
	v_mov_b32_e32 v86, v0
	v_mov_b32_e32 v87, v0
	v_mov_b32_e32 v96, v0
	v_mov_b32_e32 v97, v0
	v_mov_b32_e32 v98, v0
	v_mov_b32_e32 v99, v0
	v_mov_b32_e32 v100, v0
	v_mov_b32_e32 v101, v0
	v_mov_b32_e32 v102, v0
	v_mov_b32_e32 v103, v0
	v_mov_b32_e32 v112, v0
	v_mov_b32_e32 v113, v0
	v_mov_b32_e32 v114, v0
	v_mov_b32_e32 v115, v0
	v_mov_b32_e32 v116, v0
	v_mov_b32_e32 v117, v0
	v_mov_b32_e32 v118, v0
	v_mov_b32_e32 v119, v0
	v_mov_b32_e32 v72, v0
	v_mov_b32_e32 v73, v0
	v_mov_b32_e32 v74, v0
	v_mov_b32_e32 v75, v0
	v_mov_b32_e32 v76, v0
	v_mov_b32_e32 v77, v0
	v_mov_b32_e32 v78, v0
	v_mov_b32_e32 v79, v0
	v_mov_b32_e32 v88, v0
	v_mov_b32_e32 v89, v0
	v_mov_b32_e32 v90, v0
	v_mov_b32_e32 v91, v0
	v_mov_b32_e32 v92, v0
	v_mov_b32_e32 v93, v0
	v_mov_b32_e32 v94, v0
	v_mov_b32_e32 v95, v0
	v_mov_b32_e32 v104, v0
	v_mov_b32_e32 v105, v0
	v_mov_b32_e32 v106, v0
	v_mov_b32_e32 v107, v0
	v_mov_b32_e32 v108, v0
	v_mov_b32_e32 v109, v0
	v_mov_b32_e32 v110, v0
	v_mov_b32_e32 v111, v0
	v_mov_b32_e32 v120, v0
	v_mov_b32_e32 v121, v0
	v_mov_b32_e32 v122, v0
	v_mov_b32_e32 v123, v0
	v_mov_b32_e32 v124, v0
	v_mov_b32_e32 v125, v0
	v_mov_b32_e32 v126, v0
	v_mov_b32_e32 v127, v0
	.p2alignl 6, 3212836864

.LBB0_346:
	s_ashr_i32 s13, s12, 31
	s_lshl_b64 s[14:15], s[12:13], 20
	s_add_u32 s14, s18, s14
	s_addc_u32 s15, s19, s15
	s_and_b64 s[26:27], s[4:5], exec
	s_cselect_b32 s13, s15, s81
	s_cselect_b32 s43, s14, s80
	s_ashr_i32 s11, s10, 31
	s_lshl_b64 s[26:27], s[10:11], 20
	s_add_u32 s26, s0, s26
	s_addc_u32 s27, s1, s27
	s_and_b64 s[44:45], s[4:5], exec
	s_cselect_b32 s11, s27, s83
	s_cselect_b32 s44, s26, s82
	s_add_u32 s80, s80, 0x80080
	s_addc_u32 s81, s81, 0
	s_add_u32 s45, s82, 0x100
	v_mov_b32_e32 v0, 0
	s_addc_u32 s46, s83, 0
	s_mov_b32 s47, -2
	v_mov_b32_e32 v1, v0
	v_mov_b32_e32 v2, v0
	v_mov_b32_e32 v3, v0
	v_mov_b32_e32 v4, v0
	v_mov_b32_e32 v5, v0
	v_mov_b32_e32 v6, v0
	v_mov_b32_e32 v7, v0
	v_mov_b32_e32 v16, v0
	v_mov_b32_e32 v17, v0
	v_mov_b32_e32 v18, v0
	v_mov_b32_e32 v19, v0
	v_mov_b32_e32 v20, v0
	v_mov_b32_e32 v21, v0
	v_mov_b32_e32 v22, v0
	v_mov_b32_e32 v23, v0
	v_mov_b32_e32 v32, v0
	v_mov_b32_e32 v33, v0
	v_mov_b32_e32 v34, v0
	v_mov_b32_e32 v35, v0
	v_mov_b32_e32 v36, v0
	v_mov_b32_e32 v37, v0
	v_mov_b32_e32 v38, v0
	v_mov_b32_e32 v39, v0
	v_mov_b32_e32 v48, v0
	v_mov_b32_e32 v49, v0
	v_mov_b32_e32 v50, v0
	v_mov_b32_e32 v51, v0
	v_mov_b32_e32 v52, v0
	v_mov_b32_e32 v53, v0
	v_mov_b32_e32 v54, v0
	v_mov_b32_e32 v55, v0
	v_mov_b32_e32 v8, v0
	v_mov_b32_e32 v9, v0
	v_mov_b32_e32 v10, v0
	v_mov_b32_e32 v11, v0
	v_mov_b32_e32 v12, v0
	v_mov_b32_e32 v13, v0
	v_mov_b32_e32 v14, v0
	v_mov_b32_e32 v15, v0
	v_mov_b32_e32 v24, v0
	v_mov_b32_e32 v25, v0
	v_mov_b32_e32 v26, v0
	v_mov_b32_e32 v27, v0
	v_mov_b32_e32 v28, v0
	v_mov_b32_e32 v29, v0
	v_mov_b32_e32 v30, v0
	v_mov_b32_e32 v31, v0
	v_mov_b32_e32 v40, v0
	v_mov_b32_e32 v41, v0
	v_mov_b32_e32 v42, v0
	v_mov_b32_e32 v43, v0
	v_mov_b32_e32 v44, v0
	v_mov_b32_e32 v45, v0
	v_mov_b32_e32 v46, v0
	v_mov_b32_e32 v47, v0
	v_mov_b32_e32 v56, v0
	v_mov_b32_e32 v57, v0
	v_mov_b32_e32 v58, v0
	v_mov_b32_e32 v59, v0
	v_mov_b32_e32 v60, v0
	v_mov_b32_e32 v61, v0
	v_mov_b32_e32 v62, v0
	v_mov_b32_e32 v63, v0
	v_mov_b32_e32 v64, v0
	v_mov_b32_e32 v65, v0
	v_mov_b32_e32 v66, v0
	v_mov_b32_e32 v67, v0
	v_mov_b32_e32 v68, v0
	v_mov_b32_e32 v69, v0
	v_mov_b32_e32 v70, v0
	v_mov_b32_e32 v71, v0
	v_mov_b32_e32 v80, v0
	v_mov_b32_e32 v81, v0
	v_mov_b32_e32 v82, v0
	v_mov_b32_e32 v83, v0
	v_mov_b32_e32 v84, v0
	v_mov_b32_e32 v85, v0
	v_mov_b32_e32 v86, v0
	v_mov_b32_e32 v87, v0
	v_mov_b32_e32 v96, v0
	v_mov_b32_e32 v97, v0
	v_mov_b32_e32 v98, v0
	v_mov_b32_e32 v99, v0
	v_mov_b32_e32 v100, v0
	v_mov_b32_e32 v101, v0
	v_mov_b32_e32 v102, v0
	v_mov_b32_e32 v103, v0
	v_mov_b32_e32 v112, v0
	v_mov_b32_e32 v113, v0
	v_mov_b32_e32 v114, v0
	v_mov_b32_e32 v115, v0
	v_mov_b32_e32 v116, v0
	v_mov_b32_e32 v117, v0
	v_mov_b32_e32 v118, v0
	v_mov_b32_e32 v119, v0
	v_mov_b32_e32 v72, v0
	v_mov_b32_e32 v73, v0
	v_mov_b32_e32 v74, v0
	v_mov_b32_e32 v75, v0
	v_mov_b32_e32 v76, v0
	v_mov_b32_e32 v77, v0
	v_mov_b32_e32 v78, v0
	v_mov_b32_e32 v79, v0
	v_mov_b32_e32 v88, v0
	v_mov_b32_e32 v89, v0
	v_mov_b32_e32 v90, v0
	v_mov_b32_e32 v91, v0
	v_mov_b32_e32 v92, v0
	v_mov_b32_e32 v93, v0
	v_mov_b32_e32 v94, v0
	v_mov_b32_e32 v95, v0
	v_mov_b32_e32 v104, v0
	v_mov_b32_e32 v105, v0
	v_mov_b32_e32 v106, v0
	v_mov_b32_e32 v107, v0
	v_mov_b32_e32 v108, v0
	v_mov_b32_e32 v109, v0
	v_mov_b32_e32 v110, v0
	v_mov_b32_e32 v111, v0
	v_mov_b32_e32 v120, v0
	v_mov_b32_e32 v121, v0
	v_mov_b32_e32 v122, v0
	v_mov_b32_e32 v123, v0
	v_mov_b32_e32 v124, v0
	v_mov_b32_e32 v125, v0
	v_mov_b32_e32 v126, v0
	v_mov_b32_e32 v127, v0
	.p2alignl 6, 3212836864

.LBB0_854:
	s_ashr_i32 s15, s14, 31
	s_lshl_b64 s[24:25], s[14:15], 20
	s_add_u32 s24, s84, s24
	s_addc_u32 s25, s85, s25
	s_and_b64 s[26:27], s[6:7], exec
	s_cselect_b32 s15, s25, s49
	s_cselect_b32 s29, s24, s48
	s_ashr_i32 s13, s12, 31
	s_lshl_b64 s[26:27], s[12:13], 20
	s_add_u32 s26, s52, s26
	s_addc_u32 s27, s53, s27
	s_and_b64 s[42:43], s[6:7], exec
	s_cselect_b32 s13, s27, s71
	s_cselect_b32 s39, s26, s70
	s_add_u32 s42, s70, 0x100
	v_mov_b32_e32 v0, 0
	s_addc_u32 s43, s71, 0
	s_mov_b32 s44, -2
	s_waitcnt lgkmcnt(0)
	v_mov_b32_e32 v1, v0
	v_mov_b32_e32 v2, v0
	v_mov_b32_e32 v3, v0
	v_mov_b32_e32 v4, v0
	v_mov_b32_e32 v5, v0
	v_mov_b32_e32 v6, v0
	v_mov_b32_e32 v7, v0
	v_mov_b32_e32 v16, v0
	v_mov_b32_e32 v17, v0
	v_mov_b32_e32 v18, v0
	v_mov_b32_e32 v19, v0
	v_mov_b32_e32 v20, v0
	v_mov_b32_e32 v21, v0
	v_mov_b32_e32 v22, v0
	v_mov_b32_e32 v23, v0
	v_mov_b32_e32 v32, v0
	v_mov_b32_e32 v33, v0
	v_mov_b32_e32 v34, v0
	v_mov_b32_e32 v35, v0
	v_mov_b32_e32 v36, v0
	v_mov_b32_e32 v37, v0
	v_mov_b32_e32 v38, v0
	v_mov_b32_e32 v39, v0
	v_mov_b32_e32 v48, v0
	v_mov_b32_e32 v49, v0
	v_mov_b32_e32 v50, v0
	v_mov_b32_e32 v51, v0
	v_mov_b32_e32 v52, v0
	v_mov_b32_e32 v53, v0
	v_mov_b32_e32 v54, v0
	v_mov_b32_e32 v55, v0
	v_mov_b32_e32 v8, v0
	v_mov_b32_e32 v9, v0
	v_mov_b32_e32 v10, v0
	v_mov_b32_e32 v11, v0
	v_mov_b32_e32 v12, v0
	v_mov_b32_e32 v13, v0
	v_mov_b32_e32 v14, v0
	v_mov_b32_e32 v15, v0
	v_mov_b32_e32 v24, v0
	v_mov_b32_e32 v25, v0
	v_mov_b32_e32 v26, v0
	v_mov_b32_e32 v27, v0
	v_mov_b32_e32 v28, v0
	v_mov_b32_e32 v29, v0
	v_mov_b32_e32 v30, v0
	v_mov_b32_e32 v31, v0
	v_mov_b32_e32 v40, v0
	v_mov_b32_e32 v41, v0
	v_mov_b32_e32 v42, v0
	v_mov_b32_e32 v43, v0
	v_mov_b32_e32 v44, v0
	v_mov_b32_e32 v45, v0
	v_mov_b32_e32 v46, v0
	v_mov_b32_e32 v47, v0
	v_mov_b32_e32 v56, v0
	v_mov_b32_e32 v57, v0
	v_mov_b32_e32 v58, v0
	v_mov_b32_e32 v59, v0
	v_mov_b32_e32 v60, v0
	v_mov_b32_e32 v61, v0
	v_mov_b32_e32 v62, v0
	v_mov_b32_e32 v63, v0
	v_mov_b32_e32 v64, v0
	v_mov_b32_e32 v65, v0
	v_mov_b32_e32 v66, v0
	v_mov_b32_e32 v67, v0
	v_mov_b32_e32 v68, v0
	v_mov_b32_e32 v69, v0
	v_mov_b32_e32 v70, v0
	v_mov_b32_e32 v71, v0
	v_mov_b32_e32 v80, v0
	v_mov_b32_e32 v81, v0
	v_mov_b32_e32 v82, v0
	v_mov_b32_e32 v83, v0
	v_mov_b32_e32 v84, v0
	v_mov_b32_e32 v85, v0
	v_mov_b32_e32 v86, v0
	v_mov_b32_e32 v87, v0
	v_mov_b32_e32 v96, v0
	v_mov_b32_e32 v97, v0
	v_mov_b32_e32 v98, v0
	v_mov_b32_e32 v99, v0
	v_mov_b32_e32 v100, v0
	v_mov_b32_e32 v101, v0
	v_mov_b32_e32 v102, v0
	v_mov_b32_e32 v103, v0
	v_mov_b32_e32 v112, v0
	v_mov_b32_e32 v113, v0
	v_mov_b32_e32 v114, v0
	v_mov_b32_e32 v115, v0
	v_mov_b32_e32 v116, v0
	v_mov_b32_e32 v117, v0
	v_mov_b32_e32 v118, v0
	v_mov_b32_e32 v119, v0
	v_mov_b32_e32 v72, v0
	v_mov_b32_e32 v73, v0
	v_mov_b32_e32 v74, v0
	v_mov_b32_e32 v75, v0
	v_mov_b32_e32 v76, v0
	v_mov_b32_e32 v77, v0
	v_mov_b32_e32 v78, v0
	v_mov_b32_e32 v79, v0
	v_mov_b32_e32 v88, v0
	v_mov_b32_e32 v89, v0
	v_mov_b32_e32 v90, v0
	v_mov_b32_e32 v91, v0
	v_mov_b32_e32 v92, v0
	v_mov_b32_e32 v93, v0
	v_mov_b32_e32 v94, v0
	v_mov_b32_e32 v95, v0
	v_mov_b32_e32 v104, v0
	v_mov_b32_e32 v105, v0
	v_mov_b32_e32 v106, v0
	v_mov_b32_e32 v107, v0
	v_mov_b32_e32 v108, v0
	v_mov_b32_e32 v109, v0
	v_mov_b32_e32 v110, v0
	v_mov_b32_e32 v111, v0
	v_mov_b32_e32 v120, v0
	v_mov_b32_e32 v121, v0
	v_mov_b32_e32 v122, v0
	v_mov_b32_e32 v123, v0
	v_mov_b32_e32 v124, v0
	v_mov_b32_e32 v125, v0
	v_mov_b32_e32 v126, v0
	v_mov_b32_e32 v127, v0
	.p2alignl 6, 3212836864

.LBB0_952:
	s_ashr_i32 s15, s14, 31
	s_lshl_b64 s[24:25], s[14:15], 20
	s_add_u32 s24, s18, s24
	s_addc_u32 s25, s19, s25
	s_and_b64 s[26:27], s[4:5], exec
	s_cselect_b32 s15, s25, s29
	s_cselect_b32 s45, s24, s28
	s_ashr_i32 s13, s12, 31
	s_lshl_b64 s[26:27], s[12:13], 20
	s_add_u32 s26, s40, s26
	s_addc_u32 s27, s41, s27
	s_and_b64 s[46:47], s[4:5], exec
	s_cselect_b32 s13, s27, s31
	s_cselect_b32 s48, s26, s30
	s_add_u32 s28, s28, 0x80080
	s_addc_u32 s29, s29, 0
	s_add_u32 s49, s30, 0x100
	v_mov_b32_e32 v4, 0
	s_addc_u32 s70, s31, 0
	s_mov_b32 s71, -2
	v_mov_b32_e32 v5, v4
	v_mov_b32_e32 v6, v4
	v_mov_b32_e32 v7, v4
	v_mov_b32_e32 v12, v4
	v_mov_b32_e32 v13, v4
	v_mov_b32_e32 v14, v4
	v_mov_b32_e32 v15, v4
	v_mov_b32_e32 v20, v4
	v_mov_b32_e32 v21, v4
	v_mov_b32_e32 v22, v4
	v_mov_b32_e32 v23, v4
	v_mov_b32_e32 v28, v4
	v_mov_b32_e32 v29, v4
	v_mov_b32_e32 v30, v4
	v_mov_b32_e32 v31, v4
	v_mov_b32_e32 v36, v4
	v_mov_b32_e32 v37, v4
	v_mov_b32_e32 v38, v4
	v_mov_b32_e32 v39, v4
	v_mov_b32_e32 v44, v4
	v_mov_b32_e32 v45, v4
	v_mov_b32_e32 v46, v4
	v_mov_b32_e32 v47, v4
	v_mov_b32_e32 v52, v4
	v_mov_b32_e32 v53, v4
	v_mov_b32_e32 v54, v4
	v_mov_b32_e32 v55, v4
	v_mov_b32_e32 v60, v4
	v_mov_b32_e32 v61, v4
	v_mov_b32_e32 v62, v4
	v_mov_b32_e32 v63, v4
	v_mov_b32_e32 v0, v4
	v_mov_b32_e32 v1, v4
	v_mov_b32_e32 v2, v4
	v_mov_b32_e32 v3, v4
	v_mov_b32_e32 v8, v4
	v_mov_b32_e32 v9, v4
	v_mov_b32_e32 v10, v4
	v_mov_b32_e32 v11, v4
	v_mov_b32_e32 v16, v4
	v_mov_b32_e32 v17, v4
	v_mov_b32_e32 v18, v4
	v_mov_b32_e32 v19, v4
	v_mov_b32_e32 v24, v4
	v_mov_b32_e32 v25, v4
	v_mov_b32_e32 v26, v4
	v_mov_b32_e32 v27, v4
	v_mov_b32_e32 v32, v4
	v_mov_b32_e32 v33, v4
	v_mov_b32_e32 v34, v4
	v_mov_b32_e32 v35, v4
	v_mov_b32_e32 v40, v4
	v_mov_b32_e32 v41, v4
	v_mov_b32_e32 v42, v4
	v_mov_b32_e32 v43, v4
	v_mov_b32_e32 v48, v4
	v_mov_b32_e32 v49, v4
	v_mov_b32_e32 v50, v4
	v_mov_b32_e32 v51, v4
	v_mov_b32_e32 v56, v4
	v_mov_b32_e32 v57, v4
	v_mov_b32_e32 v58, v4
	v_mov_b32_e32 v59, v4
	v_mov_b32_e32 v68, v4
	v_mov_b32_e32 v69, v4
	v_mov_b32_e32 v70, v4
	v_mov_b32_e32 v71, v4
	v_mov_b32_e32 v76, v4
	v_mov_b32_e32 v77, v4
	v_mov_b32_e32 v78, v4
	v_mov_b32_e32 v79, v4
	v_mov_b32_e32 v88, v4
	v_mov_b32_e32 v89, v4
	v_mov_b32_e32 v90, v4
	v_mov_b32_e32 v91, v4
	v_mov_b32_e32 v92, v4
	v_mov_b32_e32 v93, v4
	v_mov_b32_e32 v94, v4
	v_mov_b32_e32 v95, v4
	v_mov_b32_e32 v104, v4
	v_mov_b32_e32 v105, v4
	v_mov_b32_e32 v106, v4
	v_mov_b32_e32 v107, v4
	v_mov_b32_e32 v108, v4
	v_mov_b32_e32 v109, v4
	v_mov_b32_e32 v110, v4
	v_mov_b32_e32 v111, v4
	v_mov_b32_e32 v120, v4
	v_mov_b32_e32 v121, v4
	v_mov_b32_e32 v122, v4
	v_mov_b32_e32 v123, v4
	v_mov_b32_e32 v124, v4
	v_mov_b32_e32 v125, v4
	v_mov_b32_e32 v126, v4
	v_mov_b32_e32 v127, v4
	v_mov_b32_e32 v64, v4
	v_mov_b32_e32 v65, v4
	v_mov_b32_e32 v66, v4
	v_mov_b32_e32 v67, v4
	v_mov_b32_e32 v72, v4
	v_mov_b32_e32 v73, v4
	v_mov_b32_e32 v74, v4
	v_mov_b32_e32 v75, v4
	v_mov_b32_e32 v80, v4
	v_mov_b32_e32 v81, v4
	v_mov_b32_e32 v82, v4
	v_mov_b32_e32 v83, v4
	v_mov_b32_e32 v84, v4
	v_mov_b32_e32 v85, v4
	v_mov_b32_e32 v86, v4
	v_mov_b32_e32 v87, v4
	v_mov_b32_e32 v96, v4
	v_mov_b32_e32 v97, v4
	v_mov_b32_e32 v98, v4
	v_mov_b32_e32 v99, v4
	v_mov_b32_e32 v100, v4
	v_mov_b32_e32 v101, v4
	v_mov_b32_e32 v102, v4
	v_mov_b32_e32 v103, v4
	v_mov_b32_e32 v112, v4
	v_mov_b32_e32 v113, v4
	v_mov_b32_e32 v114, v4
	v_mov_b32_e32 v115, v4
	v_mov_b32_e32 v116, v4
	v_mov_b32_e32 v117, v4
	v_mov_b32_e32 v118, v4
	v_mov_b32_e32 v119, v4
	.p2alignl 6, 3212836864

.LBB0_1039:
	s_add_u32 s47, s26, 0x100
	v_mov_b32_e32 v0, 0
	s_addc_u32 s48, s27, 0
	s_mov_b32 s49, -2
	v_mov_b32_e32 v1, v0
	v_mov_b32_e32 v2, v0
	v_mov_b32_e32 v3, v0
	v_mov_b32_e32 v4, v0
	v_mov_b32_e32 v5, v0
	v_mov_b32_e32 v6, v0
	v_mov_b32_e32 v7, v0
	v_mov_b32_e32 v16, v0
	v_mov_b32_e32 v17, v0
	v_mov_b32_e32 v18, v0
	v_mov_b32_e32 v19, v0
	v_mov_b32_e32 v20, v0
	v_mov_b32_e32 v21, v0
	v_mov_b32_e32 v22, v0
	v_mov_b32_e32 v23, v0
	v_mov_b32_e32 v32, v0
	v_mov_b32_e32 v33, v0
	v_mov_b32_e32 v34, v0
	v_mov_b32_e32 v35, v0
	v_mov_b32_e32 v36, v0
	v_mov_b32_e32 v37, v0
	v_mov_b32_e32 v38, v0
	v_mov_b32_e32 v39, v0
	v_mov_b32_e32 v48, v0
	v_mov_b32_e32 v49, v0
	v_mov_b32_e32 v50, v0
	v_mov_b32_e32 v51, v0
	v_mov_b32_e32 v52, v0
	v_mov_b32_e32 v53, v0
	v_mov_b32_e32 v54, v0
	v_mov_b32_e32 v55, v0
	v_mov_b32_e32 v8, v0
	v_mov_b32_e32 v9, v0
	v_mov_b32_e32 v10, v0
	v_mov_b32_e32 v11, v0
	v_mov_b32_e32 v12, v0
	v_mov_b32_e32 v13, v0
	v_mov_b32_e32 v14, v0
	v_mov_b32_e32 v15, v0
	v_mov_b32_e32 v24, v0
	v_mov_b32_e32 v25, v0
	v_mov_b32_e32 v26, v0
	v_mov_b32_e32 v27, v0
	v_mov_b32_e32 v28, v0
	v_mov_b32_e32 v29, v0
	v_mov_b32_e32 v30, v0
	v_mov_b32_e32 v31, v0
	v_mov_b32_e32 v40, v0
	v_mov_b32_e32 v41, v0
	v_mov_b32_e32 v42, v0
	v_mov_b32_e32 v43, v0
	v_mov_b32_e32 v44, v0
	v_mov_b32_e32 v45, v0
	v_mov_b32_e32 v46, v0
	v_mov_b32_e32 v47, v0
	v_mov_b32_e32 v56, v0
	v_mov_b32_e32 v57, v0
	v_mov_b32_e32 v58, v0
	v_mov_b32_e32 v59, v0
	v_mov_b32_e32 v60, v0
	v_mov_b32_e32 v61, v0
	v_mov_b32_e32 v62, v0
	v_mov_b32_e32 v63, v0
	v_mov_b32_e32 v64, v0
	v_mov_b32_e32 v65, v0
	v_mov_b32_e32 v66, v0
	v_mov_b32_e32 v67, v0
	v_mov_b32_e32 v68, v0
	v_mov_b32_e32 v69, v0
	v_mov_b32_e32 v70, v0
	v_mov_b32_e32 v71, v0
	v_mov_b32_e32 v80, v0
	v_mov_b32_e32 v81, v0
	v_mov_b32_e32 v82, v0
	v_mov_b32_e32 v83, v0
	v_mov_b32_e32 v84, v0
	v_mov_b32_e32 v85, v0
	v_mov_b32_e32 v86, v0
	v_mov_b32_e32 v87, v0
	v_mov_b32_e32 v96, v0
	v_mov_b32_e32 v97, v0
	v_mov_b32_e32 v98, v0
	v_mov_b32_e32 v99, v0
	v_mov_b32_e32 v100, v0
	v_mov_b32_e32 v101, v0
	v_mov_b32_e32 v102, v0
	v_mov_b32_e32 v103, v0
	v_mov_b32_e32 v112, v0
	v_mov_b32_e32 v113, v0
	v_mov_b32_e32 v114, v0
	v_mov_b32_e32 v115, v0
	v_mov_b32_e32 v116, v0
	v_mov_b32_e32 v117, v0
	v_mov_b32_e32 v118, v0
	v_mov_b32_e32 v119, v0
	v_mov_b32_e32 v72, v0
	v_mov_b32_e32 v73, v0
	v_mov_b32_e32 v74, v0
	v_mov_b32_e32 v75, v0
	v_mov_b32_e32 v76, v0
	v_mov_b32_e32 v77, v0
	v_mov_b32_e32 v78, v0
	v_mov_b32_e32 v79, v0
	v_mov_b32_e32 v88, v0
	v_mov_b32_e32 v89, v0
	v_mov_b32_e32 v90, v0
	v_mov_b32_e32 v91, v0
	v_mov_b32_e32 v92, v0
	v_mov_b32_e32 v93, v0
	v_mov_b32_e32 v94, v0
	v_mov_b32_e32 v95, v0
	v_mov_b32_e32 v104, v0
	v_mov_b32_e32 v105, v0
	v_mov_b32_e32 v106, v0
	v_mov_b32_e32 v107, v0
	v_mov_b32_e32 v108, v0
	v_mov_b32_e32 v109, v0
	v_mov_b32_e32 v110, v0
	v_mov_b32_e32 v111, v0
	v_mov_b32_e32 v120, v0
	v_mov_b32_e32 v121, v0
	v_mov_b32_e32 v122, v0
	v_mov_b32_e32 v123, v0
	v_mov_b32_e32 v124, v0
	v_mov_b32_e32 v125, v0
	v_mov_b32_e32 v126, v0
	v_mov_b32_e32 v127, v0
	.p2alignl 6, 3212836864
